# phase 5: drop the vmcnt(0) drain in the sub-GEMM pre-header (K loop's counted waits cover the staged tiles)
# speedup vs baseline: 1.0046x; 1.0046x over previous
; #define PG8_LDA(dst, b, h) do { _Pragma("unroll") for (int m = 0; m < 4; ++m) _Pragma("unroll") for (int k = 0; k < 2; ++k) dst[m][k] = *(const LAS bf16x8*)(lds + PG8_SA(b, h) + aoff + m * 2048 + k * 1024); } while (0)
; #define PG8_LDB(dst, b, h) do { _Pragma("unroll") for (int n = 0; n < 2; ++n) _Pragma("unroll") for (int k = 0; k < 2; ++k) dst[n][k] = *(const LAS bf16x8*)(lds + PG8_SB(b, h) + boff + n * 2048 + k * 1024); } while (0)
; #define PG8_SCHED __builtin_amdgcn_sched_barrier(0)
; #define PG8_LDA(dst, b, h) do { _Pragma("unroll") for (int m = 0; m < 4; ++m) _Pragma("unroll") for (int k = 0; k < 2; ++k) dst[m][k] = *(const LAS bf16x8*)(lds + PG8_SA(b, h) + aoff + m * 2048 + k * 1024); } while (0)
; #define PG8_LDB(dst, b, h) do { _Pragma("unroll") for (int n = 0; n < 2; ++n) _Pragma("unroll") for (int k = 0; k < 2; ++k) dst[n][k] = *(const LAS bf16x8*)(lds + PG8_SB(b, h) + boff + n * 2048 + k * 1024); } while (0)
; #define PG8_SCHED __builtin_amdgcn_sched_barrier(0)
; DI void gemm_phase_p5(LAS unsigned char* lds, const Unit u, const bf16_t* hb, const bf16_t* xn, const bf16_t* wtm, const bf16_t* wtp,
;                       char* scr, bf16_t* mixed, const float* bmerge) {
;     ...
;         const bool has_next = ui < 5;
;         nxt = has_next ? p5_sub(ui + 1, u, hb, xn, wtm, wtp) : cur;
;         const unsigned ldn = nxt.isP ? ldH : ldX;
;         const size_t hsn = nxt.isP ? hsH : hsX;
;         const int nt = cur.nt;
; #pragma unroll 1
;         for (int t = 0; t < nt; t += 2) {
;             const bool last = (t == nt - 2);
;             const char* a1 = cur.A + (size_t)(t + 1) * kstep;
;             const char* a2 = last ? nxt.A : cur.A + (size_t)(t + 2) * kstep; const char* b2 = last ? nxt.B : cur.B + (size_t)(t + 2) * kstep;
;             const unsigned ld2 = last ? ldn : ldc; const size_t hs2 = last ? hsn : hsc;
;             const char* a3 = a2 + kstep; const char* b3 = b2 + kstep;
;             PG8_LDB(B0, 0, 0); PG8_SCHED; PG8_LDA(At, 0, 0); PG8_STAGE2(PG8_SA(1, 1), a1 + hsc, rowA, ldc);
;     ...
; #pragma unroll
;         for (int a = 0; a < 2; ++a)
; #pragma unroll
;             for (int b = 0; b < 2; ++b)
; #pragma unroll
;                 for (int m = 0; m < 4; ++m)
; #pragma unroll
;                     for (int n = 0; n < 2; ++n) acc[a][b][m][n] = (f32x4){0.f, 0.f, 0.f, 0.f};
;         cur = nxt; ldc = ldn; hsc = hsn;
.LBB0_937:
	s_cmp_eq_u32 s78, 0
	s_movk_i32 s0, 0x800
	s_cselect_b32 s21, s0, 0x1e00
	s_mov_b32 s0, 0xf0000
	s_cselect_b32 s46, 0x40000, s0
	s_add_i32 s6, s10, -2
	s_lshl_b32 s0, s80, 6
	s_add_u32 s7, s50, 0x100
	s_addc_u32 s81, s51, 0
	s_add_u32 s11, s48, s0
	s_addc_u32 s50, s49, 0
	v_mad_u64_u32 v[2:3], s[0:1], s80, v179, v[182:183]
	s_add_u32 s0, s36, s11
	v_mov_b32_e32 v3, v1
	s_addc_u32 s1, s37, s50
	v_lshl_add_u64 v[4:5], s[0:1], 0, v[2:3]
	s_add_u32 s0, s36, s48
	s_addc_u32 s1, s37, s49
	s_mov_b32 s47, 0
	v_lshl_add_u64 v[132:133], s[0:1], 0, v[2:3]
	v_mov_b32_e32 v2, 0
	v_lshl_add_u64 v[130:131], v[4:5], 0, s[16:17]
	s_mov_b64 s[50:51], 0
	s_mov_b32 s52, s47
	v_mov_b32_e32 v3, v2
	v_mov_b32_e32 v4, v2
	v_mov_b32_e32 v5, v2
	v_mov_b32_e32 v6, v2
	v_mov_b32_e32 v7, v2
	v_mov_b32_e32 v8, v2
	v_mov_b32_e32 v9, v2
	v_mov_b32_e32 v18, v2
	v_mov_b32_e32 v19, v2
	v_mov_b32_e32 v20, v2
	v_mov_b32_e32 v21, v2
	v_mov_b32_e32 v22, v2
	v_mov_b32_e32 v23, v2
	v_mov_b32_e32 v24, v2
	v_mov_b32_e32 v25, v2
	v_mov_b32_e32 v34, v2
	v_mov_b32_e32 v35, v2
	v_mov_b32_e32 v36, v2
	v_mov_b32_e32 v37, v2
	v_mov_b32_e32 v38, v2
	v_mov_b32_e32 v39, v2
	v_mov_b32_e32 v40, v2
	v_mov_b32_e32 v41, v2
	v_mov_b32_e32 v50, v2
	v_mov_b32_e32 v51, v2
	v_mov_b32_e32 v52, v2
	v_mov_b32_e32 v53, v2
	v_mov_b32_e32 v54, v2
	v_mov_b32_e32 v55, v2
	v_mov_b32_e32 v56, v2
	v_mov_b32_e32 v57, v2
	v_mov_b32_e32 v10, v2
	v_mov_b32_e32 v11, v2
	v_mov_b32_e32 v12, v2
	v_mov_b32_e32 v13, v2
	v_mov_b32_e32 v14, v2
	v_mov_b32_e32 v15, v2
	v_mov_b32_e32 v16, v2
	v_mov_b32_e32 v17, v2
	v_mov_b32_e32 v26, v2
	v_mov_b32_e32 v27, v2
	v_mov_b32_e32 v28, v2
	v_mov_b32_e32 v29, v2
	v_mov_b32_e32 v30, v2
	v_mov_b32_e32 v31, v2
	v_mov_b32_e32 v32, v2
	v_mov_b32_e32 v33, v2
	v_mov_b32_e32 v42, v2
	v_mov_b32_e32 v43, v2
	v_mov_b32_e32 v44, v2
	v_mov_b32_e32 v45, v2
	v_mov_b32_e32 v46, v2
	v_mov_b32_e32 v47, v2
	v_mov_b32_e32 v48, v2
	v_mov_b32_e32 v49, v2
	v_mov_b32_e32 v58, v2
	v_mov_b32_e32 v59, v2
	v_mov_b32_e32 v60, v2
	v_mov_b32_e32 v61, v2
	v_mov_b32_e32 v62, v2
	v_mov_b32_e32 v63, v2
	v_mov_b32_e32 v64, v2
	v_mov_b32_e32 v65, v2
	v_mov_b32_e32 v66, v2
	v_mov_b32_e32 v67, v2
	v_mov_b32_e32 v68, v2
	v_mov_b32_e32 v69, v2
	v_mov_b32_e32 v70, v2
	v_mov_b32_e32 v71, v2
	v_mov_b32_e32 v72, v2
	v_mov_b32_e32 v73, v2
	v_mov_b32_e32 v82, v2
	v_mov_b32_e32 v83, v2
	v_mov_b32_e32 v84, v2
	v_mov_b32_e32 v85, v2
	v_mov_b32_e32 v86, v2
	v_mov_b32_e32 v87, v2
	v_mov_b32_e32 v88, v2
	v_mov_b32_e32 v89, v2
	v_mov_b32_e32 v98, v2
	v_mov_b32_e32 v99, v2
	v_mov_b32_e32 v100, v2
	v_mov_b32_e32 v101, v2
	v_mov_b32_e32 v102, v2
	v_mov_b32_e32 v103, v2
	v_mov_b32_e32 v104, v2
	v_mov_b32_e32 v105, v2
	v_mov_b32_e32 v114, v2
	v_mov_b32_e32 v115, v2
	v_mov_b32_e32 v116, v2
	v_mov_b32_e32 v117, v2
	v_mov_b32_e32 v118, v2
	v_mov_b32_e32 v119, v2
	v_mov_b32_e32 v120, v2
	v_mov_b32_e32 v121, v2
	v_mov_b32_e32 v74, v2
	v_mov_b32_e32 v75, v2
	v_mov_b32_e32 v76, v2
	v_mov_b32_e32 v77, v2
	v_mov_b32_e32 v78, v2
	v_mov_b32_e32 v79, v2
	v_mov_b32_e32 v80, v2
	v_mov_b32_e32 v81, v2
	v_mov_b32_e32 v90, v2
	v_mov_b32_e32 v91, v2
	v_mov_b32_e32 v92, v2
	v_mov_b32_e32 v93, v2
	v_mov_b32_e32 v94, v2
	v_mov_b32_e32 v95, v2
	v_mov_b32_e32 v96, v2
	v_mov_b32_e32 v97, v2
	v_mov_b32_e32 v106, v2
	v_mov_b32_e32 v107, v2
	v_mov_b32_e32 v108, v2
	v_mov_b32_e32 v109, v2
	v_mov_b32_e32 v110, v2
	v_mov_b32_e32 v111, v2
	v_mov_b32_e32 v112, v2
	v_mov_b32_e32 v113, v2
	v_mov_b32_e32 v122, v2
	v_mov_b32_e32 v123, v2
	v_mov_b32_e32 v124, v2
	v_mov_b32_e32 v125, v2
	v_mov_b32_e32 v126, v2
	v_mov_b32_e32 v127, v2
	v_mov_b32_e32 v128, v2
	v_mov_b32_e32 v129, v2
	v_add_u32_e32 v0, 0x10000, v183
	ds_read_b128 v[134:137], v0
	ds_read_b128 v[138:141], v0 offset:1024
	ds_read_b128 v[142:145], v0 offset:2048
	ds_read_b128 v[146:149], v0 offset:3072
